# baseline (speedup 1.0000x reference)
; __device__ __forceinline__ unsigned xb_ld(unsigned* p)              { return __hip_atomic_load(p, __ATOMIC_RELAXED, __HIP_MEMORY_SCOPE_AGENT); }
; __device__ __forceinline__ void xcd_barrier_complete(unsigned* bar, unsigned x, unsigned& nloc, unsigned& nx) {
;     ...
;     for (;;) {
;         sum = 0u; cnt = 0u; mine = 0u;
; #pragma unroll
;         for (unsigned j = 0; j < 16; ++j) { const unsigned c = xb_ld(&bar[XB_XCNT(j)]); sum += c; cnt += (c > 0u) ? 1u : 0u; mine = (j == x) ? c : mine; }
;         if (sum == G) break;
.LBB0_486:
	v_readlane_b32 s6, v251, 51
	v_readlane_b32 s7, v251, 52
	global_load_dword v2, v48, s[26:27] sc1
	s_waitcnt lgkmcnt(0)
	global_load_dword v0, v48, s[42:43] sc1
	global_load_dword v1, v48, s[40:41] sc1
	s_mov_b64 s[10:11], -1
	global_load_dword v3, v48, s[6:7] sc1
	v_readlane_b32 s6, v251, 53
	v_readlane_b32 s7, v251, 54
	s_nop 4
	global_load_dword v4, v48, s[6:7] sc1
	v_readlane_b32 s6, v251, 55
	v_readlane_b32 s7, v251, 56
	s_nop 4
	global_load_dword v5, v48, s[6:7] sc1
	v_readlane_b32 s6, v251, 57
	v_readlane_b32 s7, v251, 58
	s_nop 4
	global_load_dword v6, v48, s[6:7] sc1
	v_readlane_b32 s6, v251, 59
	v_readlane_b32 s7, v251, 60
	s_nop 4
	global_load_dword v7, v48, s[6:7] sc1
	v_readlane_b32 s6, v251, 61
	v_readlane_b32 s7, v251, 62
	s_nop 4
	global_load_dword v8, v48, s[6:7] sc1
	v_readlane_b32 s6, v251, 63
	v_readlane_b32 s7, v252, 0
	s_nop 4
	global_load_dword v9, v48, s[6:7] sc1
	v_readlane_b32 s6, v252, 1
	v_readlane_b32 s7, v252, 2
	s_nop 4
	global_load_dword v10, v48, s[6:7] sc1
	v_readlane_b32 s6, v252, 3
	v_readlane_b32 s7, v252, 4
	s_nop 4
	global_load_dword v11, v48, s[6:7] sc1
	v_readlane_b32 s6, v252, 5
	v_readlane_b32 s7, v252, 6
	s_nop 4
	global_load_dword v12, v48, s[6:7] sc1
	v_readlane_b32 s6, v252, 7
	v_readlane_b32 s7, v252, 8
	s_nop 4
	global_load_dword v13, v48, s[6:7] sc1
	v_readlane_b32 s6, v252, 9
	v_readlane_b32 s7, v252, 10
	s_nop 4
	global_load_dword v14, v48, s[6:7] sc1
	v_readlane_b32 s6, v252, 11
	v_readlane_b32 s7, v252, 12
	s_nop 4
	global_load_dword v15, v48, s[6:7] sc1
	s_mov_b64 s[6:7], -1
	s_waitcnt vmcnt(0)
	v_add_u32_e32 v16, v0, v2
	v_add_u32_e32 v16, v16, v1
	v_add_u32_e32 v16, v16, v3
	v_add_u32_e32 v16, v16, v4
	v_add_u32_e32 v16, v16, v5
	v_add_u32_e32 v16, v16, v6
	v_add_u32_e32 v16, v16, v7
	v_add_u32_e32 v16, v16, v8
	v_add_u32_e32 v16, v16, v9
	v_add_u32_e32 v16, v16, v10
	v_add_u32_e32 v16, v16, v11
	v_add_u32_e32 v16, v16, v12
	v_add_u32_e32 v16, v16, v13
	v_add_u32_e32 v16, v16, v14
	v_add_u32_e32 v16, v16, v15
	v_cmp_eq_u32_e32 vcc, s93, v16
	s_cbranch_vccnz .LBB0_485
	s_and_b32 s5, s4, 0xff
	s_cmp_eq_u32 s5, 0
	s_mov_b64 s[18:19], -1
	s_sleep 1
	s_cbranch_scc0 .LBB0_490
	v_readlane_b32 s6, v251, 49
	v_readlane_b32 s7, v251, 50
	s_nop 4
	global_load_dword v16, v48, s[6:7] sc1
	s_waitcnt vmcnt(0)
	v_cmp_eq_u32_e32 vcc, 0, v16
	s_cbranch_vccnz .LBB0_492
	s_mov_b64 s[18:19], 0
	s_mov_b64 s[6:7], -1
